# mlstm_local: mlstm_gates loads hoisted ahead of the prefetch batch with counted waits (as in mlstm_out); stale kernarg-era vmcnt(4) removed
# baseline (speedup 1.0000x reference)
.LBB0_853:
	s_mov_b64 s[10:11], s[62:63]
	s_load_dwordx4 s[40:43], s[10:11], 0x28
	s_load_dwordx2 s[2:3], s[10:11], 0xc0
	v_mov_b32_e32 v34, v208
	s_bfe_u32 s12, s23, 0x20004
	s_lshl_b32 s10, s12, 7
	v_and_b32_e32 v35, 63, v34
	v_lshl_or_b32 v7, v35, 1, s10
	v_lshlrev_b32_e32 v166, 2, v7
	v_ashrrev_i32_e32 v28, 6, v34
	s_and_b32 s13, s5, 0x780
	v_lshlrev_b32_e32 v16, 4, v28
	v_or_b32_e32 v17, 0x200, v7
	v_add_u32_e32 v6, s13, v16
	s_waitcnt lgkmcnt(0)
	v_mov_b32_e32 v0, s40
	v_mov_b32_e32 v1, s41
	v_mov_b32_e32 v2, s42
	v_mov_b32_e32 v3, s43
	v_mov_b32_e32 v32, s2
	v_mov_b32_e32 v33, s3
	v_cmp_gt_i32_e32 vcc, 0x80, v208
	s_and_saveexec_b64 s[20:21], vcc
	s_and_b32 s24, s22, 0xfffff800
	s_or_b32 s24, s24, s13
	v_add_u32_e32 v224, s24, v208
	v_ashrrev_i32_e32 v225, 31, v224
	v_lshlrev_b64 v[224:225], 5, v[224:225]
	v_lshl_add_u64 v[224:225], v[32:33], 0, v[224:225]
	s_lshl_b32 s30, s12, 2
	s_mov_b32 s31, 0
	v_lshl_add_u64 v[224:225], v[224:225], 0, s[30:31]
	s_mov_b64 s[34:35], 0x7300000
	s_or_b32 s30, s12, s36
	v_lshl_add_u64 v[226:227], v[224:225], 0, s[34:35]
	s_lshl_b64 s[30:31], s[30:31], 2
	v_lshl_add_u64 v[228:229], v[2:3], 0, s[30:31]
	global_load_dword v232, v[226:227], off offset:16
	s_nop 0
	global_load_dword v233, v[228:229], off offset:16
	v_add_co_u32_e32 v224, vcc, 0x7300000, v224
	s_nop 1
	v_addc_co_u32_e32 v225, vcc, 0, v225, vcc
	global_load_dword v234, v[224:225], off
	s_nop 0
	global_load_dword v235, v[228:229], off
	s_mov_b64 exec, s[20:21]
	v_lshl_add_u64 v[0:1], v[0:1], 0, s[14:15]
	v_lshl_add_u64 v[4:5], v[0:1], 0, v[166:167]
	v_readfirstlane_b32 s10, v0
	v_add_co_u32_e32 v0, vcc, 0x1000, v4
	v_readfirstlane_b32 s11, v1
	s_nop 0
	v_addc_co_u32_e32 v1, vcc, 0, v5, vcc
	global_load_dwordx2 v[10:11], v[0:1], off offset:2048
	v_add_co_u32_e32 v0, vcc, 0x2000, v4
	s_nop 0
	global_load_dwordx2 v[8:9], v166, s[10:11] offset:2048
	v_addc_co_u32_e32 v1, vcc, 0, v5, vcc
	global_load_dwordx2 v[12:13], v[0:1], off offset:2048
	v_add_co_u32_e32 v0, vcc, 0x3000, v4
	v_lshrrev_b32_e32 v166, 8, v17
	s_nop 0
	v_addc_co_u32_e32 v1, vcc, 0, v5, vcc
	global_load_dwordx2 v[14:15], v[0:1], off offset:2048
	v_cmp_gt_i32_e32 vcc, 3, v6
	v_and_b32_e32 v4, 0xfe, v7
	s_and_saveexec_b64 s[10:11], vcc
	s_xor_b64 s[10:11], exec, s[10:11]
	v_mov_b32_e32 v5, v167
	s_or_saveexec_b64 s[10:11], s[10:11]
	s_and_b32 s18, s22, 0xfffff800
	s_mov_b64 s[2:3], 0x74c2800
	v_add_u32_e32 v6, s18, v6
	v_lshl_add_u64 v[0:1], v[32:33], 0, s[2:3]
	v_ashrrev_i32_e32 v7, 31, v6
	v_mov_b32_e32 v24, 0
	v_mov_b32_e32 v17, 0
	v_mov_b32_e32 v19, 0
	v_mov_b32_e32 v20, 0
	s_xor_b64 exec, exec, s[10:11]
	s_cbranch_execz .LBB0_857
	v_lshl_add_u64 v[18:19], v[6:7], 0, -3
	v_alignbit_b32 v5, v19, v18, 8
	v_mad_u64_u32 v[20:21], s[20:21], v5, 49, v[166:167]
	v_mad_u32_u24 v21, v19, 49, v21
	v_lshlrev_b64 v[20:21], 17, v[20:21]
	v_lshlrev_b32_e32 v5, 9, v18
	v_lshl_add_u64 v[20:21], v[0:1], 0, v[20:21]
	v_and_b32_e32 v18, 0x1fe00, v5
	v_mov_b32_e32 v19, v167
	v_lshl_add_u64 v[18:19], v[20:21], 0, v[18:19]
	v_lshlrev_b32_e32 v20, 1, v4
	v_mov_b32_e32 v21, v167
	v_lshl_add_u64 v[18:19], v[18:19], 0, v[20:21]
	global_load_dword v17, v[18:19], off
	v_lshl_add_u64 v[18:19], v[6:7], 0, -2
	v_alignbit_b32 v5, v19, v18, 8
	v_mad_u64_u32 v[22:23], s[20:21], v5, 49, v[166:167]
	v_mad_u32_u24 v23, v19, 49, v23
	v_lshlrev_b64 v[22:23], 17, v[22:23]
	v_lshlrev_b32_e32 v5, 9, v18
	v_lshl_add_u64 v[22:23], v[0:1], 0, v[22:23]
	v_and_b32_e32 v18, 0x1fe00, v5
	v_mov_b32_e32 v19, v167
	v_lshl_add_u64 v[18:19], v[22:23], 0, v[18:19]
	v_lshl_add_u64 v[22:23], v[6:7], 0, -1
	v_alignbit_b32 v5, v23, v22, 8
	v_mad_u64_u32 v[26:27], s[20:21], v5, 49, v[166:167]
	v_mad_u32_u24 v27, v23, 49, v27
	v_lshlrev_b64 v[26:27], 17, v[26:27]
	v_lshlrev_b32_e32 v5, 9, v22
	v_lshl_add_u64 v[26:27], v[0:1], 0, v[26:27]
	v_and_b32_e32 v22, 0x1fe00, v5
	v_mov_b32_e32 v23, v167
	v_lshl_add_u64 v[22:23], v[26:27], 0, v[22:23]
	v_lshl_add_u64 v[18:19], v[18:19], 0, v[20:21]
	v_lshl_add_u64 v[20:21], v[22:23], 0, v[20:21]
	global_load_dword v19, v[18:19], off
	v_mov_b32_e32 v5, v167
	global_load_dword v20, v[20:21], off
.LBB0_857:
	s_or_b64 exec, exec, s[10:11]
	v_alignbit_b32 v18, v7, v6, 8
	v_mad_u64_u32 v[22:23], s[10:11], v18, 49, v[166:167]
	v_mad_u32_u24 v23, v7, 49, v23
	v_lshlrev_b64 v[22:23], 17, v[22:23]
	v_lshlrev_b32_e32 v6, 9, v6
	v_lshl_add_u64 v[22:23], v[0:1], 0, v[22:23]
	v_and_b32_e32 v166, 0x1e000, v6
	v_lshl_add_u64 v[6:7], v[22:23], 0, v[166:167]
	v_lshlrev_b64 v[26:27], 1, v[4:5]
	s_or_b32 s13, s18, s13
	v_lshl_add_u64 v[6:7], v[6:7], 0, v[26:27]
	global_load_dword v21, v[6:7], off
	global_load_dword v18, v[6:7], off offset:512
	global_load_dword v5, v[6:7], off offset:1024
	global_load_dword v4, v[6:7], off offset:1536
	global_load_dword v57, v[6:7], off offset:2048
	global_load_dword v54, v[6:7], off offset:2560
	global_load_dword v53, v[6:7], off offset:3072
	global_load_dword v50, v[6:7], off offset:3584
	v_add_co_u32_e32 v6, vcc, s91, v6
	v_add_u32_e32 v22, s13, v16
	s_lshr_b32 s10, s12, 1
	v_addc_co_u32_e32 v7, vcc, 0, v7, vcc
	v_ashrrev_i32_e32 v25, 31, v22
	s_or_b32 s10, s10, 4
	global_load_dword v49, v[6:7], off
	global_load_dword v45, v[6:7], off offset:512
	global_load_dword v44, v[6:7], off offset:1024
	global_load_dword v23, v[6:7], off offset:1536
	global_load_dword v42, v[6:7], off offset:2048
	global_load_dword v39, v[6:7], off offset:2560
	global_load_dword v36, v[6:7], off offset:3072
	global_load_dword v31, v[6:7], off offset:3584
	v_mov_b32_e32 v166, s10
	v_alignbit_b32 v6, v25, v22, 8
	v_mad_u64_u32 v[6:7], s[10:11], v6, 49, v[166:167]
	v_mad_u32_u24 v7, v25, 49, v7
	v_lshlrev_b64 v[6:7], 17, v[6:7]
	v_lshl_add_u64 v[0:1], v[0:1], 0, v[6:7]
	v_lshlrev_b32_e32 v6, 9, v22
	v_and_b32_e32 v166, 0x1e000, v6
	v_lshl_add_u64 v[0:1], v[0:1], 0, v[166:167]
	v_lshl_add_u64 v[0:1], v[0:1], 0, v[26:27]
	global_load_dword v22, v[0:1], off
	global_load_dword v6, v[0:1], off offset:512
	global_load_dword v7, v[0:1], off offset:1024
	global_load_dword v55, v[0:1], off offset:1536
	global_load_dword v56, v[0:1], off offset:2048
	global_load_dword v51, v[0:1], off offset:2560
	global_load_dword v52, v[0:1], off offset:3072
	global_load_dword v47, v[0:1], off offset:3584
	v_add_co_u32_e32 v0, vcc, 0x1000, v0
	s_nop 1
	v_addc_co_u32_e32 v1, vcc, 0, v1, vcc
	global_load_dword v48, v[0:1], off
	global_load_dword v46, v[0:1], off offset:512
	global_load_dword v40, v[0:1], off offset:1024
	global_load_dword v41, v[0:1], off offset:1536
	global_load_dword v37, v[0:1], off offset:2048
	global_load_dword v38, v[0:1], off offset:2560
	global_load_dword v29, v[0:1], off offset:3072
	global_load_dword v30, v[0:1], off offset:3584
	v_mov_b32_e32 v1, v208
	s_nop 0
	v_cmp_gt_i32_e64 s[10:11], s83, v1
	v_lshl_add_u32 v0, v1, 2, 0
	s_and_saveexec_b64 s[18:19], s[10:11]
	s_cbranch_execz .LBB0_861
	s_mov_b32 s0, 0xbfb8aa3b
	v_and_b32_e32 v25, 64, v214
	v_add_u32_e32 v43, -1, v214
	v_cmp_lt_i32_e32 vcc, v43, v25
	v_and_b32_e32 v24, 63, v1
	v_cmp_eq_u32_e64 s[12:13], 63, v1
	s_waitcnt vmcnt(38)
	v_add_f32_e32 v26, v232, v233
	v_mul_f32_e64 v27, |v26|, s0
	v_exp_f32_e32 v58, v27
	v_cndmask_b32_e32 v27, v43, v214, vcc
	v_lshlrev_b32_e32 v43, 2, v27
	v_min_f32_e32 v59, 0, v26
	v_add_f32_e32 v60, 1.0, v58
	v_add_f32_e32 v61, -1.0, v60
	v_frexp_mant_f32_e32 v62, v60
	v_cvt_f64_f32_e32 v[26:27], v60
	s_mov_b32 s0, 0x3f2aaaab
	v_sub_f32_e32 v63, v61, v60
	v_frexp_exp_i32_f64_e32 v26, v[26:27]
	v_cmp_gt_f32_e32 vcc, s0, v62
	v_sub_f32_e32 v61, v58, v61
	v_add_f32_e32 v27, 1.0, v63
	v_subbrev_co_u32_e32 v26, vcc, 0, v26, vcc
	v_add_f32_e32 v27, v61, v27
	v_sub_u32_e32 v61, 0, v26
	v_cvt_f32_i32_e32 v26, v26
	v_ldexp_f32 v60, v60, v61
	v_ldexp_f32 v27, v27, v61
	v_add_f32_e32 v61, -1.0, v60
	v_add_f32_e32 v62, 1.0, v60
	v_add_f32_e32 v63, 1.0, v61
	v_add_f32_e32 v64, -1.0, v62
	v_sub_f32_e32 v63, v60, v63
	v_sub_f32_e32 v60, v60, v64
	v_mul_f32_e32 v64, 0x3f317218, v26
	v_add_f32_e32 v63, v27, v63
	v_add_f32_e32 v27, v27, v60
	v_fma_f32 v60, v26, s56, -v64
	v_add_f32_e32 v65, v61, v63
	v_add_f32_e32 v66, v62, v27
	v_fmac_f32_e32 v60, 0xb102e308, v26
	v_sub_f32_e32 v26, v65, v61
	v_sub_f32_e32 v61, v66, v62
	v_rcp_f32_e32 v62, v66
	v_add_f32_e32 v67, v64, v60
	v_sub_f32_e32 v27, v27, v61
	v_sub_f32_e32 v61, v67, v64
	v_sub_f32_e32 v60, v60, v61
	v_mul_f32_e32 v61, v65, v62
	v_sub_f32_e32 v26, v63, v26
	v_mul_f32_e32 v63, v66, v61
	v_fma_f32 v64, v61, v66, -v63
	v_fmac_f32_e32 v64, v61, v27
	v_add_f32_e32 v68, v63, v64
	v_sub_f32_e32 v69, v65, v68
	v_sub_f32_e32 v63, v68, v63
	v_sub_f32_e32 v65, v65, v69
	v_sub_f32_e32 v63, v63, v64
	v_sub_f32_e32 v64, v65, v68
	v_add_f32_e32 v26, v26, v64
	v_add_f32_e32 v26, v63, v26
	v_add_f32_e32 v63, v69, v26
	v_mul_f32_e32 v64, v62, v63
	v_sub_f32_e32 v65, v69, v63
	v_mul_f32_e32 v68, v66, v64
	v_add_f32_e32 v26, v26, v65
	v_add_f32_e32 v65, v61, v64
	v_fma_f32 v66, v64, v66, -v68
	v_sub_f32_e32 v61, v65, v61
	v_fmac_f32_e32 v66, v64, v27
	v_sub_f32_e32 v27, v64, v61
	v_add_f32_e32 v61, v68, v66
	v_sub_f32_e32 v64, v61, v68
	v_sub_f32_e32 v68, v63, v61
	v_sub_f32_e32 v63, v63, v68
	v_sub_f32_e32 v61, v63, v61
	v_sub_f32_e32 v64, v64, v66
	v_add_f32_e32 v26, v26, v61
	v_add_f32_e32 v26, v64, v26
	v_add_f32_e32 v26, v68, v26
	v_mul_f32_e32 v26, v62, v26
	v_add_f32_e32 v26, v27, v26
	v_add_f32_e32 v27, v65, v26
	v_mul_f32_e32 v61, v27, v27
	v_fmamk_f32 v64, v61, 0x3e9b6dac, v217
	v_sub_f32_e32 v62, v27, v65
	v_ldexp_f32 v63, v27, 1
	v_mul_f32_e32 v27, v27, v61
	v_fmaak_f32 v61, v61, v64, 0x3f2aaada
	v_mul_f32_e32 v27, v27, v61
	v_add_f32_e32 v61, v63, v27
	v_sub_f32_e32 v26, v26, v62
	v_sub_f32_e32 v62, v61, v63
	v_ldexp_f32 v26, v26, 1
	v_sub_f32_e32 v27, v27, v62
	v_add_f32_e32 v26, v26, v27
	v_add_f32_e32 v27, v61, v26
	v_sub_f32_e32 v61, v27, v61
	v_add_f32_e32 v62, v67, v27
	v_sub_f32_e32 v26, v26, v61
	v_sub_f32_e32 v61, v62, v67
	v_sub_f32_e32 v63, v62, v61
	v_sub_f32_e32 v27, v27, v61
	v_add_f32_e32 v61, v60, v26
	v_sub_f32_e32 v63, v67, v63
	v_sub_f32_e32 v64, v61, v60
	v_add_f32_e32 v27, v27, v63
	v_sub_f32_e32 v63, v61, v64
	v_sub_f32_e32 v26, v26, v64
	v_sub_f32_e32 v60, v60, v63
	v_add_f32_e32 v27, v61, v27
	v_add_f32_e32 v26, v26, v60
	v_add_f32_e32 v60, v62, v27
	v_sub_f32_e32 v61, v60, v62
	v_sub_f32_e32 v27, v27, v61
	v_add_f32_e32 v26, v26, v27
	v_add_f32_e32 v26, v60, v26
	v_cmp_neq_f32_e32 vcc, s55, v58
	s_waitcnt vmcnt(36)
	v_add_f32_e32 v2, v234, v235
	ds_write_b32 v0, v2 offset:512
	v_cndmask_b32_e32 v26, v209, v26, vcc
	v_cmp_ngt_f32_e32 vcc, -1.0, v58
	s_nop 1
	v_cndmask_b32_e32 v26, v252, v26, vcc
	v_cmp_neq_f32_e32 vcc, -1.0, v58
	s_nop 1
	v_cndmask_b32_e32 v26, v215, v26, vcc
	v_cmp_lt_f32_e64 vcc, |v58|, s57
	s_nop 1
	v_cndmask_b32_e32 v26, v26, v58, vcc
	v_sub_f32_e32 v26, v59, v26
	ds_bpermute_b32 v27, v43, v26
	v_add_u32_e32 v43, -2, v214
	v_cmp_lt_i32_e32 vcc, v43, v25
	s_waitcnt lgkmcnt(0)
	v_add_f32_e32 v27, v26, v27
	v_cndmask_b32_e32 v43, v43, v214, vcc
	v_cmp_eq_u32_e32 vcc, 0, v24
	v_lshlrev_b32_e32 v43, 2, v43
	s_nop 0
	v_cndmask_b32_e32 v26, v27, v26, vcc
	ds_bpermute_b32 v27, v43, v26
	v_add_u32_e32 v43, -4, v214
	v_cmp_lt_i32_e32 vcc, v43, v25
	s_waitcnt lgkmcnt(0)
	v_add_f32_e32 v27, v26, v27
	v_cndmask_b32_e32 v43, v43, v214, vcc
	v_cmp_gt_u32_e32 vcc, 2, v24
	v_lshlrev_b32_e32 v43, 2, v43
	s_nop 0
	v_cndmask_b32_e32 v26, v27, v26, vcc
	ds_bpermute_b32 v27, v43, v26
	v_add_u32_e32 v43, -8, v214
	v_cmp_lt_i32_e32 vcc, v43, v25
	s_waitcnt lgkmcnt(0)
	v_add_f32_e32 v27, v26, v27
	v_cndmask_b32_e32 v43, v43, v214, vcc
	v_cmp_gt_u32_e32 vcc, 4, v24
	v_lshlrev_b32_e32 v43, 2, v43
	s_nop 0
	v_cndmask_b32_e32 v26, v27, v26, vcc
	ds_bpermute_b32 v27, v43, v26
	v_add_u32_e32 v43, -16, v214
	v_cmp_lt_i32_e32 vcc, v43, v25
	s_waitcnt lgkmcnt(0)
	v_add_f32_e32 v27, v26, v27
	v_cndmask_b32_e32 v43, v43, v214, vcc
	v_cmp_gt_u32_e32 vcc, 8, v24
	v_lshlrev_b32_e32 v43, 2, v43
	s_nop 0
	v_cndmask_b32_e32 v26, v27, v26, vcc
	ds_bpermute_b32 v27, v43, v26
	v_subrev_u32_e32 v43, 32, v214
	v_cmp_lt_i32_e32 vcc, v43, v25
	s_nop 1
	v_cndmask_b32_e32 v25, v43, v214, vcc
	v_lshlrev_b32_e32 v43, 2, v25
	s_waitcnt lgkmcnt(0)
	v_add_f32_e32 v25, v26, v27
	v_cmp_gt_u32_e32 vcc, 16, v24
	s_nop 1
	v_cndmask_b32_e32 v25, v25, v26, vcc
	ds_bpermute_b32 v26, v43, v25
	v_cmp_gt_u32_e32 vcc, 32, v24
	s_waitcnt lgkmcnt(0)
	v_add_f32_e32 v2, v25, v26
	s_and_saveexec_b64 s[20:21], s[12:13]
	ds_write_b32 v167, v2 offset:1024
	s_or_b64 exec, exec, s[20:21]
	v_cndmask_b32_e32 v24, v2, v25, vcc
